# gate|up K-loop back edge: counter/pointer updates and the loop head's scalar selects issued inside the last MFMA block; only compare+branch after the barrier
# baseline (speedup 1.0000x reference)
; #define PG8_STAGE(bufoff, gbase, voff) do { _Pragma("unroll") for (int _i = 0; _i < 2; ++_i) \
;         __builtin_amdgcn_global_load_lds((const unsigned*)((const char*)(gbase) + (voff)[_i]), (PG8_LAS unsigned*)(lds + (bufoff) + ldsw + _i * 8192), 16, 0, 0); } while (0)
; #define PG8_STAGEA(bufoff, gbase, voff) do { _Pragma("unroll") for (int _i = 0; _i < 2; ++_i) \
;         __builtin_amdgcn_global_load_lds((const unsigned*)((const char*)(gbase) + (voff)[_i]), (PG8_LAS unsigned*)(lds + (bufoff) + ldsw + _i * 8192), 16, 0, A_AUX); } while (0)
; #define PG8_LDA(dst, b, h) do { _Pragma("unroll") for (int m = 0; m < 4; ++m) _Pragma("unroll") for (int k = 0; k < 2; ++k) dst[m][k] = *(const PG8_LAS bf16x8*)(lds + PG8_SA(b, h) + aoff + m * 2048 + k * 1024); } while (0)
; #define PG8_LDB(dst, b, h) do { _Pragma("unroll") for (int n = 0; n < 2; ++n) _Pragma("unroll") for (int k = 0; k < 2; ++k) dst[n][k] = *(const PG8_LAS bf16x8*)(lds + PG8_SB(b, h) + boff + n * 2048 + k * 1024); } while (0)
; #define PG8_MMA(ai, bj, At, Bt) do { __builtin_amdgcn_s_setprio(1); _Pragma("unroll") for (int m = 0; m < 4; ++m) _Pragma("unroll") for (int n = 0; n < 2; ++n) _Pragma("unroll") for (int k = 0; k < 2; ++k) \
;         acc[ai][bj][m][n] = __builtin_amdgcn_mfma_f32_16x16x32_bf16(Bt[n][k], At[m][k], acc[ai][bj][m][n], 0, 0, 0); __builtin_amdgcn_s_setprio(0); } while (0)
; #define PG8_WAIT_V(n) asm volatile("s_waitcnt vmcnt(" #n ")" ::: "memory")
; #define PG8_WAIT_L(n) asm volatile("s_waitcnt lgkmcnt(" #n ")" ::: "memory")
; #define PG8_BAR __builtin_amdgcn_s_barrier()
; #define PG8_SCHED __builtin_amdgcn_sched_barrier(0)
;     ...
;             PG8_LDB(B0, 0, 0); PG8_LDB(B1, 0, 1); PG8_SCHED; PG8_LDA(At, 0, 0); PG8_STAGEA(PG8_SA(1, 1), a1 + hstep, voffA);
;             PG8_WAIT_V(8); PG8_WAIT_L(0); PG8_BAR; PG8_MMA(0, 0, At, B0); PG8_MMA(0, 1, At, B1); PG8_BAR; PG8_SCHED;
;             PG8_LDA(At, 0, 1); PG8_STAGE(PG8_SB(0, 0), b2, voffB); PG8_STAGE(PG8_SB(0, 1), b2 + hstep, voffB); PG8_STAGEA(PG8_SA(0, 0), a2, voffA);
;             PG8_WAIT_V(8); PG8_WAIT_L(0); PG8_BAR; PG8_MMA(1, 0, At, B0); PG8_MMA(1, 1, At, B1); PG8_BAR; PG8_SCHED;
.LBB0_579:
	s_ashr_i32 s45, s44, 31
	s_lshl_b64 s[16:17], s[44:45], 19
	s_add_u32 s46, s97, s16
	s_addc_u32 s47, s29, s17
	s_and_b64 s[16:17], s[40:41], exec
	s_cselect_b32 s16, s47, s51
	s_cselect_b32 s17, s46, s50
	s_ashr_i32 s43, s42, 31
	s_lshl_b64 s[48:49], s[42:43], 19
	s_add_u32 s48, s23, s48
	s_addc_u32 s49, s56, s49
	s_and_b64 s[54:55], s[40:41], exec
	s_cselect_b32 s43, s49, s53
	s_cselect_b32 s45, s48, s52
	s_add_u32 s50, s50, 0x40080
	s_addc_u32 s51, s51, 0
	s_add_u32 s73, s52, 0x100
	s_addc_u32 s76, s53, 0
	s_mov_b32 vcc_lo, -2
	s_add_u32 s52, s50, 0xfffc0080
	s_addc_u32 s53, s51, -1
	s_add_i32 s70, 0, 0x10000
	s_cmp_eq_u32 vcc_lo, 12
	s_cselect_b32 s55, s16, s53
	s_cselect_b32 s54, s17, s52
	s_cselect_b32 s53, s43, s76
	s_cselect_b32 s52, s45, s73
	s_add_i32 vcc_hi, 0, 0x14000
	v_add_u32_e32 v140, s70, v143
	ds_read_b128 v[146:149], v140
	ds_read_b128 v[150:153], v140 offset:1024
	ds_read_b128 v[154:157], v140 offset:2048
	ds_read_b128 v[158:161], v140 offset:3072
	v_add_u32_e32 v140, vcc_hi, v143
	ds_read_b128 v[174:177], v140
	ds_read_b128 v[178:181], v140 offset:1024
	ds_read_b128 v[182:185], v140 offset:2048
	ds_read_b128 v[186:189], v140 offset:3072
	v_lshl_add_u64 v[140:141], s[50:51], 0, v[136:137]
	s_add_i32 m0, s58, 0xc000
	ds_read_b128 v[200:203], v145
	ds_read_b128 v[208:211], v145 offset:1024
	ds_read_b128 v[212:215], v145 offset:2048
	ds_read_b128 v[216:219], v145 offset:3072
	ds_read_b128 v[220:223], v145 offset:4096
	ds_read_b128 v[224:227], v145 offset:5120
	ds_read_b128 v[228:231], v145 offset:6144
	ds_read_b128 v[232:235], v145 offset:7168
	global_load_lds_dwordx4 v[140:141], off
	v_lshl_add_u64 v[140:141], s[50:51], 0, v[138:139]
	s_add_i32 m0, s58, 0xe000
	s_nop 0
	global_load_lds_dwordx4 v[140:141], off
	s_waitcnt vmcnt(8)
	s_waitcnt lgkmcnt(0)
	s_barrier
	s_setprio 1
	s_waitcnt lgkmcnt(0)
	v_mfma_f32_16x16x32_bf16 v[126:129], v[146:149], v[200:203], 0
	v_mfma_f32_16x16x32_bf16 v[122:125], v[154:157], v[200:203], 0
	v_mfma_f32_16x16x32_bf16 v[110:113], v[146:149], v[212:215], 0
	v_mfma_f32_16x16x32_bf16 v[106:109], v[154:157], v[212:215], 0
	v_mfma_f32_16x16x32_bf16 v[94:97], v[146:149], v[220:223], 0
	v_mfma_f32_16x16x32_bf16 v[90:93], v[154:157], v[220:223], 0
	v_mfma_f32_16x16x32_bf16 v[78:81], v[146:149], v[228:231], 0
	v_mfma_f32_16x16x32_bf16 v[74:77], v[154:157], v[228:231], 0
	v_mfma_f32_16x16x32_bf16 v[126:129], v[150:153], v[208:211], v[126:129]
	v_mfma_f32_16x16x32_bf16 v[122:125], v[158:161], v[208:211], v[122:125]
	v_mfma_f32_16x16x32_bf16 v[110:113], v[150:153], v[216:219], v[110:113]
	v_mfma_f32_16x16x32_bf16 v[106:109], v[158:161], v[216:219], v[106:109]
	v_mfma_f32_16x16x32_bf16 v[94:97], v[150:153], v[224:227], v[94:97]
	v_mfma_f32_16x16x32_bf16 v[90:93], v[158:161], v[224:227], v[90:93]
	v_mfma_f32_16x16x32_bf16 v[78:81], v[150:153], v[232:235], v[78:81]
	v_mfma_f32_16x16x32_bf16 v[74:77], v[158:161], v[232:235], v[74:77]
	s_setprio 0
	s_setprio 1
	v_mfma_f32_16x16x32_bf16 v[118:121], v[174:177], v[200:203], 0
	v_mfma_f32_16x16x32_bf16 v[114:117], v[182:185], v[200:203], 0
	v_mfma_f32_16x16x32_bf16 v[102:105], v[174:177], v[212:215], 0
	v_mfma_f32_16x16x32_bf16 v[98:101], v[182:185], v[212:215], 0
	v_mfma_f32_16x16x32_bf16 v[86:89], v[174:177], v[220:223], 0
	v_mfma_f32_16x16x32_bf16 v[82:85], v[182:185], v[220:223], 0
	v_mfma_f32_16x16x32_bf16 v[70:73], v[174:177], v[228:231], 0
	v_mfma_f32_16x16x32_bf16 v[66:69], v[182:185], v[228:231], 0
	v_mfma_f32_16x16x32_bf16 v[118:121], v[178:181], v[208:211], v[118:121]
	v_mfma_f32_16x16x32_bf16 v[114:117], v[186:189], v[208:211], v[114:117]
	v_mfma_f32_16x16x32_bf16 v[102:105], v[178:181], v[216:219], v[102:105]
	v_mfma_f32_16x16x32_bf16 v[98:101], v[186:189], v[216:219], v[98:101]
	v_mfma_f32_16x16x32_bf16 v[86:89], v[178:181], v[224:227], v[86:89]
	v_mfma_f32_16x16x32_bf16 v[82:85], v[186:189], v[224:227], v[82:85]
	v_mfma_f32_16x16x32_bf16 v[70:73], v[178:181], v[232:235], v[70:73]
	v_mfma_f32_16x16x32_bf16 v[66:69], v[186:189], v[232:235], v[66:69]
	s_setprio 0
	s_barrier
	s_add_i32 s70, s70, s57
	v_lshl_add_u64 v[140:141], s[52:53], 0, v[0:1]
	s_mov_b32 m0, s70
	ds_read_b128 v[200:203], v145 offset:16384
	ds_read_b128 v[208:211], v145 offset:17408
	ds_read_b128 v[212:215], v145 offset:18432
	ds_read_b128 v[216:219], v145 offset:19456
	ds_read_b128 v[220:223], v145 offset:20480
	ds_read_b128 v[224:227], v145 offset:21504
	ds_read_b128 v[228:231], v145 offset:22528
	ds_read_b128 v[232:235], v145 offset:23552
	global_load_lds_dwordx4 v[140:141], off
	s_add_i32 m0, s70, 0x2000
	s_add_u32 s70, s52, 0x40000
	v_lshl_add_u64 v[190:191], s[52:53], 0, v[130:131]
	s_addc_u32 s71, s53, 0
	s_add_i32 vcc_hi, vcc_hi, s57
	global_load_lds_dwordx4 v[190:191], off
	v_lshl_add_u64 v[236:237], s[70:71], 0, v[0:1]
	s_mov_b32 m0, vcc_hi
	v_lshl_add_u64 v[238:239], s[54:55], 0, v[132:133]
	global_load_lds_dwordx4 v[236:237], off
	v_lshl_add_u64 v[236:237], s[70:71], 0, v[130:131]
	s_add_i32 m0, vcc_hi, 0x2000
	s_nop 0
	global_load_lds_dwordx4 v[236:237], off
	v_lshl_add_u64 v[236:237], s[54:55], 0, v[134:135]
	s_mov_b32 m0, s58
	s_nop 0
	global_load_lds_dwordx4 v[236:237], off
	s_mov_b32 m0, s59
	s_nop 0
	global_load_lds_dwordx4 v[238:239], off
	s_waitcnt vmcnt(8)
	s_waitcnt lgkmcnt(0)
	s_barrier
; #define PG8_STAGEA(bufoff, gbase, voff) do { _Pragma("unroll") for (int _i = 0; _i < 2; ++_i) \
;         __builtin_amdgcn_global_load_lds((const unsigned*)((const char*)(gbase) + (voff)[_i]), (PG8_LAS unsigned*)(lds + (bufoff) + ldsw + _i * 8192), 16, 0, A_AUX); } while (0)
; #define PG8_LDA(dst, b, h) do { _Pragma("unroll") for (int m = 0; m < 4; ++m) _Pragma("unroll") for (int k = 0; k < 2; ++k) dst[m][k] = *(const PG8_LAS bf16x8*)(lds + PG8_SA(b, h) + aoff + m * 2048 + k * 1024); } while (0)
; #define PG8_LDB(dst, b, h) do { _Pragma("unroll") for (int n = 0; n < 2; ++n) _Pragma("unroll") for (int k = 0; k < 2; ++k) dst[n][k] = *(const PG8_LAS bf16x8*)(lds + PG8_SB(b, h) + boff + n * 2048 + k * 1024); } while (0)
; #define PG8_MMA(ai, bj, At, Bt) do { __builtin_amdgcn_s_setprio(1); _Pragma("unroll") for (int m = 0; m < 4; ++m) _Pragma("unroll") for (int n = 0; n < 2; ++n) _Pragma("unroll") for (int k = 0; k < 2; ++k) \
;         acc[ai][bj][m][n] = __builtin_amdgcn_mfma_f32_16x16x32_bf16(Bt[n][k], At[m][k], acc[ai][bj][m][n], 0, 0, 0); __builtin_amdgcn_s_setprio(0); } while (0)
; #define PG8_WAIT_V(n) asm volatile("s_waitcnt vmcnt(" #n ")" ::: "memory")
; #define PG8_WAIT_L(n) asm volatile("s_waitcnt lgkmcnt(" #n ")" ::: "memory")
; #define PG8_BAR __builtin_amdgcn_s_barrier()
; #define PG8_SCHED __builtin_amdgcn_sched_barrier(0)
;     ...
;             PG8_WAIT_V(8); PG8_WAIT_L(0); PG8_BAR; PG8_MMA(1, 0, At, B0); PG8_MMA(1, 1, At, B1); PG8_BAR; PG8_SCHED;
;             PG8_LDB(B0, 1, 0); PG8_LDB(B1, 1, 1); PG8_SCHED; PG8_LDA(At, 1, 0); PG8_STAGEA(PG8_SA(0, 1), a2 + hstep, voffA);
;             PG8_WAIT_V(8); PG8_WAIT_L(0); PG8_BAR; PG8_MMA(0, 0, At, B0); PG8_MMA(0, 1, At, B1); PG8_BAR; PG8_SCHED;
	s_setprio 1
	s_waitcnt lgkmcnt(0)
	v_mfma_f32_16x16x32_bf16 v[62:65], v[146:149], v[200:203], 0
	v_mfma_f32_16x16x32_bf16 v[58:61], v[154:157], v[200:203], 0
	v_mfma_f32_16x16x32_bf16 v[46:49], v[146:149], v[212:215], 0
	v_mfma_f32_16x16x32_bf16 v[42:45], v[154:157], v[212:215], 0
	v_mfma_f32_16x16x32_bf16 v[30:33], v[146:149], v[220:223], 0
	v_mfma_f32_16x16x32_bf16 v[26:29], v[154:157], v[220:223], 0
	v_mfma_f32_16x16x32_bf16 v[14:17], v[146:149], v[228:231], 0
	v_mfma_f32_16x16x32_bf16 v[10:13], v[154:157], v[228:231], 0
	v_mfma_f32_16x16x32_bf16 v[62:65], v[150:153], v[208:211], v[62:65]
	v_mfma_f32_16x16x32_bf16 v[58:61], v[158:161], v[208:211], v[58:61]
	v_mfma_f32_16x16x32_bf16 v[46:49], v[150:153], v[216:219], v[46:49]
	v_mfma_f32_16x16x32_bf16 v[42:45], v[158:161], v[216:219], v[42:45]
	v_mfma_f32_16x16x32_bf16 v[30:33], v[150:153], v[224:227], v[30:33]
	v_mfma_f32_16x16x32_bf16 v[26:29], v[158:161], v[224:227], v[26:29]
	v_mfma_f32_16x16x32_bf16 v[14:17], v[150:153], v[232:235], v[14:17]
	v_mfma_f32_16x16x32_bf16 v[10:13], v[158:161], v[232:235], v[10:13]
	s_setprio 0
	s_setprio 1
	v_mfma_f32_16x16x32_bf16 v[54:57], v[174:177], v[200:203], 0
	v_mfma_f32_16x16x32_bf16 v[50:53], v[182:185], v[200:203], 0
	v_mfma_f32_16x16x32_bf16 v[38:41], v[174:177], v[212:215], 0
	v_mfma_f32_16x16x32_bf16 v[34:37], v[182:185], v[212:215], 0
	v_mfma_f32_16x16x32_bf16 v[22:25], v[174:177], v[220:223], 0
	v_mfma_f32_16x16x32_bf16 v[18:21], v[182:185], v[220:223], 0
	v_mfma_f32_16x16x32_bf16 v[6:9], v[174:177], v[228:231], 0
	v_mfma_f32_16x16x32_bf16 v[2:5], v[182:185], v[228:231], 0
	v_mfma_f32_16x16x32_bf16 v[54:57], v[178:181], v[208:211], v[54:57]
	v_mfma_f32_16x16x32_bf16 v[50:53], v[186:189], v[208:211], v[50:53]
	v_mfma_f32_16x16x32_bf16 v[38:41], v[178:181], v[216:219], v[38:41]
	v_mfma_f32_16x16x32_bf16 v[34:37], v[186:189], v[216:219], v[34:37]
	v_mfma_f32_16x16x32_bf16 v[22:25], v[178:181], v[224:227], v[22:25]
	v_mfma_f32_16x16x32_bf16 v[18:21], v[186:189], v[224:227], v[18:21]
	v_mfma_f32_16x16x32_bf16 v[6:9], v[178:181], v[232:235], v[6:9]
	v_mfma_f32_16x16x32_bf16 v[2:5], v[186:189], v[232:235], v[2:5]
	s_setprio 0
	s_barrier
	s_add_i32 s70, 0, 0x18000
	s_add_i32 s71, 0, 0x1c000
	v_add_u32_e32 v158, s70, v143
	v_add_u32_e32 v186, s71, v143
	ds_read_b128 v[146:149], v158
	ds_read_b128 v[150:153], v158 offset:1024
	ds_read_b128 v[154:157], v158 offset:2048
	ds_read_b128 v[158:161], v158 offset:3072
	ds_read_b128 v[174:177], v186
	ds_read_b128 v[178:181], v186 offset:1024
	ds_read_b128 v[182:185], v186 offset:2048
	ds_read_b128 v[186:189], v186 offset:3072
	s_add_u32 s54, s54, 0x40000
	s_addc_u32 s55, s55, 0
	s_mov_b32 m0, s60
	v_lshl_add_u64 v[240:241], s[54:55], 0, v[134:135]
	ds_read_b128 v[200:203], v145 offset:32768
	ds_read_b128 v[208:211], v145 offset:33792
	ds_read_b128 v[212:215], v145 offset:34816
	ds_read_b128 v[216:219], v145 offset:35840
	ds_read_b128 v[220:223], v145 offset:36864
	ds_read_b128 v[224:227], v145 offset:37888
	ds_read_b128 v[228:231], v145 offset:38912
	ds_read_b128 v[232:235], v145 offset:39936
	global_load_lds_dwordx4 v[240:241], off
	v_lshl_add_u64 v[240:241], s[54:55], 0, v[132:133]
	s_mov_b32 m0, s61
	s_nop 0
	global_load_lds_dwordx4 v[240:241], off
	s_waitcnt vmcnt(8)
	s_waitcnt lgkmcnt(0)
	s_barrier
	s_setprio 1
	s_waitcnt lgkmcnt(0)
	v_mfma_f32_16x16x32_bf16 v[126:129], v[146:149], v[200:203], v[126:129]
	v_mfma_f32_16x16x32_bf16 v[122:125], v[154:157], v[200:203], v[122:125]
	v_mfma_f32_16x16x32_bf16 v[110:113], v[146:149], v[212:215], v[110:113]
	v_mfma_f32_16x16x32_bf16 v[106:109], v[154:157], v[212:215], v[106:109]
	v_mfma_f32_16x16x32_bf16 v[94:97], v[146:149], v[220:223], v[94:97]
	v_mfma_f32_16x16x32_bf16 v[90:93], v[154:157], v[220:223], v[90:93]
	v_mfma_f32_16x16x32_bf16 v[78:81], v[146:149], v[228:231], v[78:81]
	v_mfma_f32_16x16x32_bf16 v[74:77], v[154:157], v[228:231], v[74:77]
	v_mfma_f32_16x16x32_bf16 v[126:129], v[150:153], v[208:211], v[126:129]
	v_mfma_f32_16x16x32_bf16 v[122:125], v[158:161], v[208:211], v[122:125]
	v_mfma_f32_16x16x32_bf16 v[110:113], v[150:153], v[216:219], v[110:113]
	v_mfma_f32_16x16x32_bf16 v[106:109], v[158:161], v[216:219], v[106:109]
	v_mfma_f32_16x16x32_bf16 v[94:97], v[150:153], v[224:227], v[94:97]
	v_mfma_f32_16x16x32_bf16 v[90:93], v[158:161], v[224:227], v[90:93]
	v_mfma_f32_16x16x32_bf16 v[78:81], v[150:153], v[232:235], v[78:81]
	v_mfma_f32_16x16x32_bf16 v[74:77], v[158:161], v[232:235], v[74:77]
	s_setprio 0
	s_setprio 1
	v_mfma_f32_16x16x32_bf16 v[118:121], v[174:177], v[200:203], v[118:121]
	v_mfma_f32_16x16x32_bf16 v[114:117], v[182:185], v[200:203], v[114:117]
	v_mfma_f32_16x16x32_bf16 v[102:105], v[174:177], v[212:215], v[102:105]
	v_mfma_f32_16x16x32_bf16 v[98:101], v[182:185], v[212:215], v[98:101]
	v_mfma_f32_16x16x32_bf16 v[86:89], v[174:177], v[220:223], v[86:89]
	v_mfma_f32_16x16x32_bf16 v[82:85], v[182:185], v[220:223], v[82:85]
	v_mfma_f32_16x16x32_bf16 v[70:73], v[174:177], v[228:231], v[70:73]
	v_mfma_f32_16x16x32_bf16 v[66:69], v[182:185], v[228:231], v[66:69]
	v_mfma_f32_16x16x32_bf16 v[118:121], v[178:181], v[208:211], v[118:121]
	v_mfma_f32_16x16x32_bf16 v[114:117], v[186:189], v[208:211], v[114:117]
	v_mfma_f32_16x16x32_bf16 v[102:105], v[178:181], v[216:219], v[102:105]
	v_mfma_f32_16x16x32_bf16 v[98:101], v[186:189], v[216:219], v[98:101]
	v_mfma_f32_16x16x32_bf16 v[86:89], v[178:181], v[224:227], v[86:89]
	v_mfma_f32_16x16x32_bf16 v[82:85], v[186:189], v[224:227], v[82:85]
	v_mfma_f32_16x16x32_bf16 v[70:73], v[178:181], v[232:235], v[70:73]
	v_mfma_f32_16x16x32_bf16 v[66:69], v[186:189], v[232:235], v[66:69]
	s_setprio 0
	s_barrier
; #define PG8_STAGE(bufoff, gbase, voff) do { _Pragma("unroll") for (int _i = 0; _i < 2; ++_i) \
;         __builtin_amdgcn_global_load_lds((const unsigned*)((const char*)(gbase) + (voff)[_i]), (PG8_LAS unsigned*)(lds + (bufoff) + ldsw + _i * 8192), 16, 0, 0); } while (0)
; #define PG8_STAGEA(bufoff, gbase, voff) do { _Pragma("unroll") for (int _i = 0; _i < 2; ++_i) \
;         __builtin_amdgcn_global_load_lds((const unsigned*)((const char*)(gbase) + (voff)[_i]), (PG8_LAS unsigned*)(lds + (bufoff) + ldsw + _i * 8192), 16, 0, A_AUX); } while (0)
; #define PG8_LDA(dst, b, h) do { _Pragma("unroll") for (int m = 0; m < 4; ++m) _Pragma("unroll") for (int k = 0; k < 2; ++k) dst[m][k] = *(const PG8_LAS bf16x8*)(lds + PG8_SA(b, h) + aoff + m * 2048 + k * 1024); } while (0)
; #define PG8_MMA(ai, bj, At, Bt) do { __builtin_amdgcn_s_setprio(1); _Pragma("unroll") for (int m = 0; m < 4; ++m) _Pragma("unroll") for (int n = 0; n < 2; ++n) _Pragma("unroll") for (int k = 0; k < 2; ++k) \
;         acc[ai][bj][m][n] = __builtin_amdgcn_mfma_f32_16x16x32_bf16(Bt[n][k], At[m][k], acc[ai][bj][m][n], 0, 0, 0); __builtin_amdgcn_s_setprio(0); } while (0)
; #define PG8_WAIT_V(n) asm volatile("s_waitcnt vmcnt(" #n ")" ::: "memory")
; #define PG8_WAIT_L(n) asm volatile("s_waitcnt lgkmcnt(" #n ")" ::: "memory")
; #define PG8_BAR __builtin_amdgcn_s_barrier()
; #define PG8_SCHED __builtin_amdgcn_sched_barrier(0)
;     ...
;         for (int t = 0; t < nt; t += 2) {
;             const bool last = (t == nt - 2);
;             const char* a1 = cA + (size_t)(t + 1) * kstep;
;             const char* a2 = last ? nA : cA + (size_t)(t + 2) * kstep; const char* b2 = last ? nB : cB + (size_t)(t + 2) * kstep;
;             const char* a3 = a2 + kstep; const char* b3 = b2 + kstep;
;     ...
;             PG8_LDA(At, 1, 1); PG8_STAGE(PG8_SB(1, 0), b3, voffB); PG8_STAGE(PG8_SB(1, 1), b3 + hstep, voffB); PG8_STAGEA(PG8_SA(1, 0), a3, voffA);
;             PG8_WAIT_V(8); PG8_WAIT_L(0); PG8_BAR; PG8_MMA(1, 0, At, B0); PG8_MMA(1, 1, At, B1); PG8_BAR; PG8_SCHED;
	s_add_i32 s54, s70, s57
	v_lshl_add_u64 v[140:141], v[140:141], 0, s[8:9]
	s_mov_b32 m0, s54
	ds_read_b128 v[200:203], v145 offset:49152
	ds_read_b128 v[208:211], v145 offset:50176
	ds_read_b128 v[212:215], v145 offset:51200
	ds_read_b128 v[216:219], v145 offset:52224
	ds_read_b128 v[220:223], v145 offset:53248
	ds_read_b128 v[224:227], v145 offset:54272
	ds_read_b128 v[228:231], v145 offset:55296
	ds_read_b128 v[232:235], v145 offset:56320
	global_load_lds_dwordx4 v[140:141], off
	s_add_i32 m0, s54, 0x2000
	s_add_u32 s52, s52, 0x40080
	v_lshl_add_u64 v[140:141], v[190:191], 0, s[8:9]
	s_addc_u32 s53, s53, 0
	s_add_i32 s54, s71, s57
	global_load_lds_dwordx4 v[140:141], off
	v_lshl_add_u64 v[140:141], s[52:53], 0, v[0:1]
	s_mov_b32 m0, s54
	s_nop 0
	global_load_lds_dwordx4 v[140:141], off
	v_lshl_add_u64 v[140:141], s[52:53], 0, v[130:131]
	s_add_i32 m0, s54, 0x2000
	s_nop 0
	global_load_lds_dwordx4 v[140:141], off
	v_lshl_add_u64 v[140:141], v[236:237], 0, s[8:9]
	s_mov_b32 m0, s62
	s_nop 0
	global_load_lds_dwordx4 v[140:141], off
	v_lshl_add_u64 v[140:141], v[238:239], 0, s[8:9]
	s_mov_b32 m0, s63
	s_nop 0
	global_load_lds_dwordx4 v[140:141], off
	s_waitcnt vmcnt(8)
	s_waitcnt lgkmcnt(0)
	s_barrier
	s_setprio 1
	s_waitcnt lgkmcnt(0)
	v_mfma_f32_16x16x32_bf16 v[62:65], v[146:149], v[200:203], v[62:65]
	v_mfma_f32_16x16x32_bf16 v[58:61], v[154:157], v[200:203], v[58:61]
	v_mfma_f32_16x16x32_bf16 v[46:49], v[146:149], v[212:215], v[46:49]
	v_mfma_f32_16x16x32_bf16 v[42:45], v[154:157], v[212:215], v[42:45]
	v_mfma_f32_16x16x32_bf16 v[30:33], v[146:149], v[220:223], v[30:33]
	v_mfma_f32_16x16x32_bf16 v[26:29], v[154:157], v[220:223], v[26:29]
	v_mfma_f32_16x16x32_bf16 v[14:17], v[146:149], v[228:231], v[14:17]
	v_mfma_f32_16x16x32_bf16 v[10:13], v[154:157], v[228:231], v[10:13]
	v_mfma_f32_16x16x32_bf16 v[62:65], v[150:153], v[208:211], v[62:65]
	v_mfma_f32_16x16x32_bf16 v[58:61], v[158:161], v[208:211], v[58:61]
	v_mfma_f32_16x16x32_bf16 v[46:49], v[150:153], v[216:219], v[46:49]
	v_mfma_f32_16x16x32_bf16 v[42:45], v[158:161], v[216:219], v[42:45]
	v_mfma_f32_16x16x32_bf16 v[30:33], v[150:153], v[224:227], v[30:33]
	v_mfma_f32_16x16x32_bf16 v[26:29], v[158:161], v[224:227], v[26:29]
	v_mfma_f32_16x16x32_bf16 v[14:17], v[150:153], v[232:235], v[14:17]
	v_mfma_f32_16x16x32_bf16 v[10:13], v[158:161], v[232:235], v[10:13]
	s_setprio 0
	s_setprio 1
	v_mfma_f32_16x16x32_bf16 v[54:57], v[174:177], v[200:203], v[54:57]
	v_mfma_f32_16x16x32_bf16 v[50:53], v[182:185], v[200:203], v[50:53]
	v_mfma_f32_16x16x32_bf16 v[38:41], v[174:177], v[212:215], v[38:41]
	v_mfma_f32_16x16x32_bf16 v[34:37], v[182:185], v[212:215], v[34:37]
	s_add_i32 vcc_lo, vcc_lo, 2
	s_add_u32 s50, s50, 0x100
	s_addc_u32 s51, s51, 0
	s_add_u32 s73, s73, 0x100
	s_addc_u32 s76, s76, 0
	s_add_u32 s52, s50, 0xfffc0080
	s_addc_u32 s53, s51, -1
	s_add_i32 s70, 0, 0x10000
	s_cmp_eq_u32 vcc_lo, 12
	s_cselect_b32 s55, s16, s53
	s_cselect_b32 s54, s17, s52
	s_cselect_b32 s53, s43, s76
	s_cselect_b32 s52, s45, s73
	s_add_i32 vcc_hi, 0, 0x14000
	v_mfma_f32_16x16x32_bf16 v[22:25], v[174:177], v[220:223], v[22:25]
	v_mfma_f32_16x16x32_bf16 v[18:21], v[182:185], v[220:223], v[18:21]
	v_mfma_f32_16x16x32_bf16 v[6:9], v[174:177], v[228:231], v[6:9]
	v_mfma_f32_16x16x32_bf16 v[2:5], v[182:185], v[228:231], v[2:5]
	v_mfma_f32_16x16x32_bf16 v[54:57], v[178:181], v[208:211], v[54:57]
	v_mfma_f32_16x16x32_bf16 v[50:53], v[186:189], v[208:211], v[50:53]
	v_mfma_f32_16x16x32_bf16 v[38:41], v[178:181], v[216:219], v[38:41]
	v_mfma_f32_16x16x32_bf16 v[34:37], v[186:189], v[216:219], v[34:37]
	v_mfma_f32_16x16x32_bf16 v[22:25], v[178:181], v[224:227], v[22:25]
	v_mfma_f32_16x16x32_bf16 v[18:21], v[186:189], v[224:227], v[18:21]
	v_mfma_f32_16x16x32_bf16 v[6:9], v[178:181], v[232:235], v[6:9]
	v_mfma_f32_16x16x32_bf16 v[2:5], v[186:189], v[232:235], v[2:5]
	s_setprio 0
	s_barrier
.LBB0_580:
	v_add_u32_e32 v140, s70, v143
	ds_read_b128 v[146:149], v140
	ds_read_b128 v[150:153], v140 offset:1024
	ds_read_b128 v[154:157], v140 offset:2048
	ds_read_b128 v[158:161], v140 offset:3072
	v_add_u32_e32 v140, vcc_hi, v143
	ds_read_b128 v[174:177], v140
	ds_read_b128 v[178:181], v140 offset:1024
	ds_read_b128 v[182:185], v140 offset:2048
	ds_read_b128 v[186:189], v140 offset:3072
	v_lshl_add_u64 v[140:141], s[50:51], 0, v[136:137]
	s_add_i32 m0, s58, 0xc000
	ds_read_b128 v[200:203], v145
	ds_read_b128 v[208:211], v145 offset:1024
	ds_read_b128 v[212:215], v145 offset:2048
	ds_read_b128 v[216:219], v145 offset:3072
	ds_read_b128 v[220:223], v145 offset:4096
	ds_read_b128 v[224:227], v145 offset:5120
	ds_read_b128 v[228:231], v145 offset:6144
	ds_read_b128 v[232:235], v145 offset:7168
	global_load_lds_dwordx4 v[140:141], off
	v_lshl_add_u64 v[140:141], s[50:51], 0, v[138:139]
	s_add_i32 m0, s58, 0xe000
	s_nop 0
	global_load_lds_dwordx4 v[140:141], off
	s_waitcnt vmcnt(8)
	s_waitcnt lgkmcnt(0)
	s_barrier
; #define PG8_STAGE(bufoff, gbase, voff) do { _Pragma("unroll") for (int _i = 0; _i < 2; ++_i) \
;         __builtin_amdgcn_global_load_lds((const unsigned*)((const char*)(gbase) + (voff)[_i]), (PG8_LAS unsigned*)(lds + (bufoff) + ldsw + _i * 8192), 16, 0, 0); } while (0)
; #define PG8_STAGEA(bufoff, gbase, voff) do { _Pragma("unroll") for (int _i = 0; _i < 2; ++_i) \
;         __builtin_amdgcn_global_load_lds((const unsigned*)((const char*)(gbase) + (voff)[_i]), (PG8_LAS unsigned*)(lds + (bufoff) + ldsw + _i * 8192), 16, 0, A_AUX); } while (0)
; #define PG8_LDA(dst, b, h) do { _Pragma("unroll") for (int m = 0; m < 4; ++m) _Pragma("unroll") for (int k = 0; k < 2; ++k) dst[m][k] = *(const PG8_LAS bf16x8*)(lds + PG8_SA(b, h) + aoff + m * 2048 + k * 1024); } while (0)
; #define PG8_MMA(ai, bj, At, Bt) do { __builtin_amdgcn_s_setprio(1); _Pragma("unroll") for (int m = 0; m < 4; ++m) _Pragma("unroll") for (int n = 0; n < 2; ++n) _Pragma("unroll") for (int k = 0; k < 2; ++k) \
;         acc[ai][bj][m][n] = __builtin_amdgcn_mfma_f32_16x16x32_bf16(Bt[n][k], At[m][k], acc[ai][bj][m][n], 0, 0, 0); __builtin_amdgcn_s_setprio(0); } while (0)
; #define PG8_WAIT_V(n) asm volatile("s_waitcnt vmcnt(" #n ")" ::: "memory")
; #define PG8_WAIT_L(n) asm volatile("s_waitcnt lgkmcnt(" #n ")" ::: "memory")
; #define PG8_BAR __builtin_amdgcn_s_barrier()
; #define PG8_SCHED __builtin_amdgcn_sched_barrier(0)
;     ...
;             PG8_WAIT_V(8); PG8_WAIT_L(0); PG8_BAR; PG8_MMA(0, 0, At, B0); PG8_MMA(0, 1, At, B1); PG8_BAR; PG8_SCHED;
;             PG8_LDA(At, 0, 1); PG8_STAGE(PG8_SB(0, 0), b2, voffB); PG8_STAGE(PG8_SB(0, 1), b2 + hstep, voffB); PG8_STAGEA(PG8_SA(0, 0), a2, voffA);
;             PG8_WAIT_V(8); PG8_WAIT_L(0); PG8_BAR; PG8_MMA(1, 0, At, B0); PG8_MMA(1, 1, At, B1); PG8_BAR; PG8_SCHED;
	s_setprio 1
	s_waitcnt lgkmcnt(0)
	v_mfma_f32_16x16x32_bf16 v[126:129], v[146:149], v[200:203], v[126:129]
	v_mfma_f32_16x16x32_bf16 v[122:125], v[154:157], v[200:203], v[122:125]
	v_mfma_f32_16x16x32_bf16 v[110:113], v[146:149], v[212:215], v[110:113]
	v_mfma_f32_16x16x32_bf16 v[106:109], v[154:157], v[212:215], v[106:109]
	v_mfma_f32_16x16x32_bf16 v[94:97], v[146:149], v[220:223], v[94:97]
	v_mfma_f32_16x16x32_bf16 v[90:93], v[154:157], v[220:223], v[90:93]
	v_mfma_f32_16x16x32_bf16 v[78:81], v[146:149], v[228:231], v[78:81]
	v_mfma_f32_16x16x32_bf16 v[74:77], v[154:157], v[228:231], v[74:77]
	v_mfma_f32_16x16x32_bf16 v[126:129], v[150:153], v[208:211], v[126:129]
	v_mfma_f32_16x16x32_bf16 v[122:125], v[158:161], v[208:211], v[122:125]
	v_mfma_f32_16x16x32_bf16 v[110:113], v[150:153], v[216:219], v[110:113]
	v_mfma_f32_16x16x32_bf16 v[106:109], v[158:161], v[216:219], v[106:109]
	v_mfma_f32_16x16x32_bf16 v[94:97], v[150:153], v[224:227], v[94:97]
	v_mfma_f32_16x16x32_bf16 v[90:93], v[158:161], v[224:227], v[90:93]
	v_mfma_f32_16x16x32_bf16 v[78:81], v[150:153], v[232:235], v[78:81]
	v_mfma_f32_16x16x32_bf16 v[74:77], v[158:161], v[232:235], v[74:77]
	s_setprio 0
	s_setprio 1
	v_mfma_f32_16x16x32_bf16 v[118:121], v[174:177], v[200:203], v[118:121]
	v_mfma_f32_16x16x32_bf16 v[114:117], v[182:185], v[200:203], v[114:117]
	v_mfma_f32_16x16x32_bf16 v[102:105], v[174:177], v[212:215], v[102:105]
	v_mfma_f32_16x16x32_bf16 v[98:101], v[182:185], v[212:215], v[98:101]
	v_mfma_f32_16x16x32_bf16 v[86:89], v[174:177], v[220:223], v[86:89]
	v_mfma_f32_16x16x32_bf16 v[82:85], v[182:185], v[220:223], v[82:85]
	v_mfma_f32_16x16x32_bf16 v[70:73], v[174:177], v[228:231], v[70:73]
	v_mfma_f32_16x16x32_bf16 v[66:69], v[182:185], v[228:231], v[66:69]
	v_mfma_f32_16x16x32_bf16 v[118:121], v[178:181], v[208:211], v[118:121]
	v_mfma_f32_16x16x32_bf16 v[114:117], v[186:189], v[208:211], v[114:117]
	v_mfma_f32_16x16x32_bf16 v[102:105], v[178:181], v[216:219], v[102:105]
	v_mfma_f32_16x16x32_bf16 v[98:101], v[186:189], v[216:219], v[98:101]
	v_mfma_f32_16x16x32_bf16 v[86:89], v[178:181], v[224:227], v[86:89]
	v_mfma_f32_16x16x32_bf16 v[82:85], v[186:189], v[224:227], v[82:85]
	v_mfma_f32_16x16x32_bf16 v[70:73], v[178:181], v[232:235], v[70:73]
	v_mfma_f32_16x16x32_bf16 v[66:69], v[186:189], v[232:235], v[66:69]
	s_setprio 0
	s_barrier
	s_add_i32 s70, s70, s57
	v_lshl_add_u64 v[140:141], s[52:53], 0, v[0:1]
	s_mov_b32 m0, s70
	ds_read_b128 v[200:203], v145 offset:16384
	ds_read_b128 v[208:211], v145 offset:17408
	ds_read_b128 v[212:215], v145 offset:18432
	ds_read_b128 v[216:219], v145 offset:19456
	ds_read_b128 v[220:223], v145 offset:20480
	ds_read_b128 v[224:227], v145 offset:21504
	ds_read_b128 v[228:231], v145 offset:22528
	ds_read_b128 v[232:235], v145 offset:23552
	global_load_lds_dwordx4 v[140:141], off
	s_add_i32 m0, s70, 0x2000
	s_add_u32 s70, s52, 0x40000
	v_lshl_add_u64 v[190:191], s[52:53], 0, v[130:131]
	s_addc_u32 s71, s53, 0
	s_add_i32 vcc_hi, vcc_hi, s57
	global_load_lds_dwordx4 v[190:191], off
	v_lshl_add_u64 v[236:237], s[70:71], 0, v[0:1]
	s_mov_b32 m0, vcc_hi
	v_lshl_add_u64 v[238:239], s[54:55], 0, v[132:133]
	global_load_lds_dwordx4 v[236:237], off
	v_lshl_add_u64 v[236:237], s[70:71], 0, v[130:131]
	s_add_i32 m0, vcc_hi, 0x2000
	s_nop 0
	global_load_lds_dwordx4 v[236:237], off
	v_lshl_add_u64 v[236:237], s[54:55], 0, v[134:135]
	s_mov_b32 m0, s58
	s_nop 0
	global_load_lds_dwordx4 v[236:237], off
	s_mov_b32 m0, s59
	s_nop 0
	global_load_lds_dwordx4 v[238:239], off
	s_waitcnt vmcnt(8)
	s_waitcnt lgkmcnt(0)
	s_barrier
	s_setprio 1
	s_waitcnt lgkmcnt(0)
	v_mfma_f32_16x16x32_bf16 v[62:65], v[146:149], v[200:203], v[62:65]
	v_mfma_f32_16x16x32_bf16 v[58:61], v[154:157], v[200:203], v[58:61]
	v_mfma_f32_16x16x32_bf16 v[46:49], v[146:149], v[212:215], v[46:49]
	v_mfma_f32_16x16x32_bf16 v[42:45], v[154:157], v[212:215], v[42:45]
	v_mfma_f32_16x16x32_bf16 v[30:33], v[146:149], v[220:223], v[30:33]
	v_mfma_f32_16x16x32_bf16 v[26:29], v[154:157], v[220:223], v[26:29]
	v_mfma_f32_16x16x32_bf16 v[14:17], v[146:149], v[228:231], v[14:17]
	v_mfma_f32_16x16x32_bf16 v[10:13], v[154:157], v[228:231], v[10:13]
	v_mfma_f32_16x16x32_bf16 v[62:65], v[150:153], v[208:211], v[62:65]
	v_mfma_f32_16x16x32_bf16 v[58:61], v[158:161], v[208:211], v[58:61]
	v_mfma_f32_16x16x32_bf16 v[46:49], v[150:153], v[216:219], v[46:49]
	v_mfma_f32_16x16x32_bf16 v[42:45], v[158:161], v[216:219], v[42:45]
	v_mfma_f32_16x16x32_bf16 v[30:33], v[150:153], v[224:227], v[30:33]
	v_mfma_f32_16x16x32_bf16 v[26:29], v[158:161], v[224:227], v[26:29]
	v_mfma_f32_16x16x32_bf16 v[14:17], v[150:153], v[232:235], v[14:17]
	v_mfma_f32_16x16x32_bf16 v[10:13], v[158:161], v[232:235], v[10:13]
	s_setprio 0
	s_setprio 1
	v_mfma_f32_16x16x32_bf16 v[54:57], v[174:177], v[200:203], v[54:57]
	v_mfma_f32_16x16x32_bf16 v[50:53], v[182:185], v[200:203], v[50:53]
	v_mfma_f32_16x16x32_bf16 v[38:41], v[174:177], v[212:215], v[38:41]
	v_mfma_f32_16x16x32_bf16 v[34:37], v[182:185], v[212:215], v[34:37]
	v_mfma_f32_16x16x32_bf16 v[22:25], v[174:177], v[220:223], v[22:25]
	v_mfma_f32_16x16x32_bf16 v[18:21], v[182:185], v[220:223], v[18:21]
	v_mfma_f32_16x16x32_bf16 v[6:9], v[174:177], v[228:231], v[6:9]
	v_mfma_f32_16x16x32_bf16 v[2:5], v[182:185], v[228:231], v[2:5]
	v_mfma_f32_16x16x32_bf16 v[54:57], v[178:181], v[208:211], v[54:57]
	v_mfma_f32_16x16x32_bf16 v[50:53], v[186:189], v[208:211], v[50:53]
	v_mfma_f32_16x16x32_bf16 v[38:41], v[178:181], v[216:219], v[38:41]
	v_mfma_f32_16x16x32_bf16 v[34:37], v[186:189], v[216:219], v[34:37]
	v_mfma_f32_16x16x32_bf16 v[22:25], v[178:181], v[224:227], v[22:25]
	v_mfma_f32_16x16x32_bf16 v[18:21], v[186:189], v[224:227], v[18:21]
	v_mfma_f32_16x16x32_bf16 v[6:9], v[178:181], v[232:235], v[6:9]
	v_mfma_f32_16x16x32_bf16 v[2:5], v[186:189], v[232:235], v[2:5]
	s_setprio 0
	s_barrier
; #define PG8_STAGEA(bufoff, gbase, voff) do { _Pragma("unroll") for (int _i = 0; _i < 2; ++_i) \
;         __builtin_amdgcn_global_load_lds((const unsigned*)((const char*)(gbase) + (voff)[_i]), (PG8_LAS unsigned*)(lds + (bufoff) + ldsw + _i * 8192), 16, 0, A_AUX); } while (0)
; #define PG8_LDA(dst, b, h) do { _Pragma("unroll") for (int m = 0; m < 4; ++m) _Pragma("unroll") for (int k = 0; k < 2; ++k) dst[m][k] = *(const PG8_LAS bf16x8*)(lds + PG8_SA(b, h) + aoff + m * 2048 + k * 1024); } while (0)
; #define PG8_LDB(dst, b, h) do { _Pragma("unroll") for (int n = 0; n < 2; ++n) _Pragma("unroll") for (int k = 0; k < 2; ++k) dst[n][k] = *(const PG8_LAS bf16x8*)(lds + PG8_SB(b, h) + boff + n * 2048 + k * 1024); } while (0)
; #define PG8_MMA(ai, bj, At, Bt) do { __builtin_amdgcn_s_setprio(1); _Pragma("unroll") for (int m = 0; m < 4; ++m) _Pragma("unroll") for (int n = 0; n < 2; ++n) _Pragma("unroll") for (int k = 0; k < 2; ++k) \
;         acc[ai][bj][m][n] = __builtin_amdgcn_mfma_f32_16x16x32_bf16(Bt[n][k], At[m][k], acc[ai][bj][m][n], 0, 0, 0); __builtin_amdgcn_s_setprio(0); } while (0)
; #define PG8_WAIT_V(n) asm volatile("s_waitcnt vmcnt(" #n ")" ::: "memory")
; #define PG8_WAIT_L(n) asm volatile("s_waitcnt lgkmcnt(" #n ")" ::: "memory")
; #define PG8_BAR __builtin_amdgcn_s_barrier()
; #define PG8_SCHED __builtin_amdgcn_sched_barrier(0)
;     ...
;             PG8_LDB(B0, 1, 0); PG8_LDB(B1, 1, 1); PG8_SCHED; PG8_LDA(At, 1, 0); PG8_STAGEA(PG8_SA(0, 1), a2 + hstep, voffA);
;             PG8_WAIT_V(8); PG8_WAIT_L(0); PG8_BAR; PG8_MMA(0, 0, At, B0); PG8_MMA(0, 1, At, B1); PG8_BAR; PG8_SCHED;
	s_add_i32 s70, 0, 0x18000
	s_add_i32 s71, 0, 0x1c000
	v_add_u32_e32 v158, s70, v143
	v_add_u32_e32 v186, s71, v143
	ds_read_b128 v[146:149], v158
	ds_read_b128 v[150:153], v158 offset:1024
	ds_read_b128 v[154:157], v158 offset:2048
	ds_read_b128 v[158:161], v158 offset:3072
	ds_read_b128 v[174:177], v186
	ds_read_b128 v[178:181], v186 offset:1024
	ds_read_b128 v[182:185], v186 offset:2048
	ds_read_b128 v[186:189], v186 offset:3072
	s_add_u32 s54, s54, 0x40000
	s_addc_u32 s55, s55, 0
	s_mov_b32 m0, s60
	v_lshl_add_u64 v[240:241], s[54:55], 0, v[134:135]
	ds_read_b128 v[200:203], v145 offset:32768
	ds_read_b128 v[208:211], v145 offset:33792
	ds_read_b128 v[212:215], v145 offset:34816
	ds_read_b128 v[216:219], v145 offset:35840
	ds_read_b128 v[220:223], v145 offset:36864
	ds_read_b128 v[224:227], v145 offset:37888
	ds_read_b128 v[228:231], v145 offset:38912
	ds_read_b128 v[232:235], v145 offset:39936
	global_load_lds_dwordx4 v[240:241], off
	v_lshl_add_u64 v[240:241], s[54:55], 0, v[132:133]
	s_mov_b32 m0, s61
	s_nop 0
	global_load_lds_dwordx4 v[240:241], off
	s_waitcnt vmcnt(8)
	s_waitcnt lgkmcnt(0)
	s_barrier
	s_setprio 1
	s_waitcnt lgkmcnt(0)
	v_mfma_f32_16x16x32_bf16 v[126:129], v[146:149], v[200:203], v[126:129]
	v_mfma_f32_16x16x32_bf16 v[122:125], v[154:157], v[200:203], v[122:125]
	v_mfma_f32_16x16x32_bf16 v[110:113], v[146:149], v[212:215], v[110:113]
	v_mfma_f32_16x16x32_bf16 v[106:109], v[154:157], v[212:215], v[106:109]
	v_mfma_f32_16x16x32_bf16 v[94:97], v[146:149], v[220:223], v[94:97]
	v_mfma_f32_16x16x32_bf16 v[90:93], v[154:157], v[220:223], v[90:93]
	v_mfma_f32_16x16x32_bf16 v[78:81], v[146:149], v[228:231], v[78:81]
	v_mfma_f32_16x16x32_bf16 v[74:77], v[154:157], v[228:231], v[74:77]
	v_mfma_f32_16x16x32_bf16 v[126:129], v[150:153], v[208:211], v[126:129]
	v_mfma_f32_16x16x32_bf16 v[122:125], v[158:161], v[208:211], v[122:125]
	v_mfma_f32_16x16x32_bf16 v[110:113], v[150:153], v[216:219], v[110:113]
	v_mfma_f32_16x16x32_bf16 v[106:109], v[158:161], v[216:219], v[106:109]
	v_mfma_f32_16x16x32_bf16 v[94:97], v[150:153], v[224:227], v[94:97]
	v_mfma_f32_16x16x32_bf16 v[90:93], v[158:161], v[224:227], v[90:93]
	v_mfma_f32_16x16x32_bf16 v[78:81], v[150:153], v[232:235], v[78:81]
	v_mfma_f32_16x16x32_bf16 v[74:77], v[158:161], v[232:235], v[74:77]
	s_setprio 0
	s_setprio 1
	v_mfma_f32_16x16x32_bf16 v[118:121], v[174:177], v[200:203], v[118:121]
	v_mfma_f32_16x16x32_bf16 v[114:117], v[182:185], v[200:203], v[114:117]
	v_mfma_f32_16x16x32_bf16 v[102:105], v[174:177], v[212:215], v[102:105]
	v_mfma_f32_16x16x32_bf16 v[98:101], v[182:185], v[212:215], v[98:101]
	v_mfma_f32_16x16x32_bf16 v[86:89], v[174:177], v[220:223], v[86:89]
	v_mfma_f32_16x16x32_bf16 v[82:85], v[182:185], v[220:223], v[82:85]
	v_mfma_f32_16x16x32_bf16 v[70:73], v[174:177], v[228:231], v[70:73]
	v_mfma_f32_16x16x32_bf16 v[66:69], v[182:185], v[228:231], v[66:69]
	v_mfma_f32_16x16x32_bf16 v[118:121], v[178:181], v[208:211], v[118:121]
	v_mfma_f32_16x16x32_bf16 v[114:117], v[186:189], v[208:211], v[114:117]
	v_mfma_f32_16x16x32_bf16 v[102:105], v[178:181], v[216:219], v[102:105]
	v_mfma_f32_16x16x32_bf16 v[98:101], v[186:189], v[216:219], v[98:101]
	v_mfma_f32_16x16x32_bf16 v[86:89], v[178:181], v[224:227], v[86:89]
	v_mfma_f32_16x16x32_bf16 v[82:85], v[186:189], v[224:227], v[82:85]
	v_mfma_f32_16x16x32_bf16 v[70:73], v[178:181], v[232:235], v[70:73]
	v_mfma_f32_16x16x32_bf16 v[66:69], v[186:189], v[232:235], v[66:69]
	s_setprio 0
	s_barrier
; #define PG8_STAGE(bufoff, gbase, voff) do { _Pragma("unroll") for (int _i = 0; _i < 2; ++_i) \
;         __builtin_amdgcn_global_load_lds((const unsigned*)((const char*)(gbase) + (voff)[_i]), (PG8_LAS unsigned*)(lds + (bufoff) + ldsw + _i * 8192), 16, 0, 0); } while (0)
; #define PG8_STAGEA(bufoff, gbase, voff) do { _Pragma("unroll") for (int _i = 0; _i < 2; ++_i) \
;         __builtin_amdgcn_global_load_lds((const unsigned*)((const char*)(gbase) + (voff)[_i]), (PG8_LAS unsigned*)(lds + (bufoff) + ldsw + _i * 8192), 16, 0, A_AUX); } while (0)
; #define PG8_LDA(dst, b, h) do { _Pragma("unroll") for (int m = 0; m < 4; ++m) _Pragma("unroll") for (int k = 0; k < 2; ++k) dst[m][k] = *(const PG8_LAS bf16x8*)(lds + PG8_SA(b, h) + aoff + m * 2048 + k * 1024); } while (0)
; #define PG8_WAIT_V(n) asm volatile("s_waitcnt vmcnt(" #n ")" ::: "memory")
; #define PG8_BAR __builtin_amdgcn_s_barrier()
;     ...
;         for (int t = 0; t < nt; t += 2) {
;             const bool last = (t == nt - 2);
;             const char* a1 = cA + (size_t)(t + 1) * kstep;
;             const char* a2 = last ? nA : cA + (size_t)(t + 2) * kstep; const char* b2 = last ? nB : cB + (size_t)(t + 2) * kstep;
;             const char* a3 = a2 + kstep; const char* b3 = b2 + kstep;
;             if (last && has_next) S.a_ready(nxt);
;             if constexpr (SP2) {
;             PG8_LDB(B0, 0, 0); PG8_LDB(B1, 0, 1); PG8_SCHED; PG8_LDA(At, 0, 0); PG8_STAGEA(PG8_SA(1, 1), a1 + hstep, voffA);
;             PG8_WAIT_V(8); PG8_WAIT_L(0); PG8_BAR; PG8_MMA(0, 0, At, B0); PG8_MMA(0, 1, At, B1); PG8_BAR; PG8_SCHED;
;             PG8_LDA(At, 0, 1); PG8_STAGE(PG8_SB(0, 0), b2, voffB); PG8_STAGE(PG8_SB(0, 1), b2 + hstep, voffB); PG8_STAGEA(PG8_SA(0, 0), a2, voffA);
;             PG8_WAIT_V(8); PG8_WAIT_L(0); PG8_BAR; PG8_MMA(1, 0, At, B0); PG8_MMA(1, 1, At, B1); PG8_BAR; PG8_SCHED;
;             PG8_LDB(B0, 1, 0); PG8_LDB(B1, 1, 1); PG8_SCHED; PG8_LDA(At, 1, 0); PG8_STAGEA(PG8_SA(0, 1), a2 + hstep, voffA);
;             PG8_WAIT_V(8); PG8_WAIT_L(0); PG8_BAR; PG8_MMA(0, 0, At, B0); PG8_MMA(0, 1, At, B1); PG8_BAR; PG8_SCHED;
;             PG8_LDA(At, 1, 1); PG8_STAGE(PG8_SB(1, 0), b3, voffB); PG8_STAGE(PG8_SB(1, 1), b3 + hstep, voffB); PG8_STAGEA(PG8_SA(1, 0), a3, voffA);
;             PG8_WAIT_V(8); PG8_WAIT_L(0); PG8_BAR; PG8_MMA(1, 0, At, B0); PG8_MMA(1, 1, At, B1); PG8_BAR; PG8_SCHED;
	s_add_i32 s54, s70, s57
	v_lshl_add_u64 v[140:141], v[140:141], 0, s[8:9]
	s_mov_b32 m0, s54
	ds_read_b128 v[200:203], v145 offset:49152
	ds_read_b128 v[208:211], v145 offset:50176
	ds_read_b128 v[212:215], v145 offset:51200
	ds_read_b128 v[216:219], v145 offset:52224
	ds_read_b128 v[220:223], v145 offset:53248
	ds_read_b128 v[224:227], v145 offset:54272
	ds_read_b128 v[228:231], v145 offset:55296
	ds_read_b128 v[232:235], v145 offset:56320
	global_load_lds_dwordx4 v[140:141], off
	s_add_i32 m0, s54, 0x2000
	s_add_u32 s52, s52, 0x40080
	v_lshl_add_u64 v[140:141], v[190:191], 0, s[8:9]
	s_addc_u32 s53, s53, 0
	s_add_i32 s54, s71, s57
	global_load_lds_dwordx4 v[140:141], off
	v_lshl_add_u64 v[140:141], s[52:53], 0, v[0:1]
	s_mov_b32 m0, s54
	s_nop 0
	global_load_lds_dwordx4 v[140:141], off
	v_lshl_add_u64 v[140:141], s[52:53], 0, v[130:131]
	s_add_i32 m0, s54, 0x2000
	s_nop 0
	global_load_lds_dwordx4 v[140:141], off
	v_lshl_add_u64 v[140:141], v[236:237], 0, s[8:9]
	s_mov_b32 m0, s62
	s_nop 0
	global_load_lds_dwordx4 v[140:141], off
	v_lshl_add_u64 v[140:141], v[238:239], 0, s[8:9]
	s_mov_b32 m0, s63
	s_nop 0
	global_load_lds_dwordx4 v[140:141], off
	s_waitcnt vmcnt(8)
	s_waitcnt lgkmcnt(0)
	s_barrier
	s_setprio 1
	s_waitcnt lgkmcnt(0)
	v_mfma_f32_16x16x32_bf16 v[62:65], v[146:149], v[200:203], v[62:65]
	v_mfma_f32_16x16x32_bf16 v[58:61], v[154:157], v[200:203], v[58:61]
	v_mfma_f32_16x16x32_bf16 v[46:49], v[146:149], v[212:215], v[46:49]
	v_mfma_f32_16x16x32_bf16 v[42:45], v[154:157], v[212:215], v[42:45]
	v_mfma_f32_16x16x32_bf16 v[30:33], v[146:149], v[220:223], v[30:33]
	v_mfma_f32_16x16x32_bf16 v[26:29], v[154:157], v[220:223], v[26:29]
	v_mfma_f32_16x16x32_bf16 v[14:17], v[146:149], v[228:231], v[14:17]
	v_mfma_f32_16x16x32_bf16 v[10:13], v[154:157], v[228:231], v[10:13]
	v_mfma_f32_16x16x32_bf16 v[62:65], v[150:153], v[208:211], v[62:65]
	v_mfma_f32_16x16x32_bf16 v[58:61], v[158:161], v[208:211], v[58:61]
	v_mfma_f32_16x16x32_bf16 v[46:49], v[150:153], v[216:219], v[46:49]
	v_mfma_f32_16x16x32_bf16 v[42:45], v[158:161], v[216:219], v[42:45]
	v_mfma_f32_16x16x32_bf16 v[30:33], v[150:153], v[224:227], v[30:33]
	v_mfma_f32_16x16x32_bf16 v[26:29], v[158:161], v[224:227], v[26:29]
	v_mfma_f32_16x16x32_bf16 v[14:17], v[150:153], v[232:235], v[14:17]
	v_mfma_f32_16x16x32_bf16 v[10:13], v[158:161], v[232:235], v[10:13]
	s_setprio 0
	s_setprio 1
	v_mfma_f32_16x16x32_bf16 v[54:57], v[174:177], v[200:203], v[54:57]
	v_mfma_f32_16x16x32_bf16 v[50:53], v[182:185], v[200:203], v[50:53]
	v_mfma_f32_16x16x32_bf16 v[38:41], v[174:177], v[212:215], v[38:41]
	v_mfma_f32_16x16x32_bf16 v[34:37], v[182:185], v[212:215], v[34:37]
	s_add_i32 vcc_lo, vcc_lo, 2
	s_add_u32 s50, s50, 0x100
	s_addc_u32 s51, s51, 0
	s_add_u32 s73, s73, 0x100
	s_addc_u32 s76, s76, 0
	s_add_u32 s52, s50, 0xfffc0080
	s_addc_u32 s53, s51, -1
	s_add_i32 s70, 0, 0x10000
	s_cmp_eq_u32 vcc_lo, 12
	s_cselect_b32 s55, s16, s53
	s_cselect_b32 s54, s17, s52
	s_cselect_b32 s53, s43, s76
	s_cselect_b32 s52, s45, s73
	s_add_i32 vcc_hi, 0, 0x14000
	v_mfma_f32_16x16x32_bf16 v[22:25], v[174:177], v[220:223], v[22:25]
	v_mfma_f32_16x16x32_bf16 v[18:21], v[182:185], v[220:223], v[18:21]
	v_mfma_f32_16x16x32_bf16 v[6:9], v[174:177], v[228:231], v[6:9]
	v_mfma_f32_16x16x32_bf16 v[2:5], v[182:185], v[228:231], v[2:5]
	v_mfma_f32_16x16x32_bf16 v[54:57], v[178:181], v[208:211], v[54:57]
	v_mfma_f32_16x16x32_bf16 v[50:53], v[186:189], v[208:211], v[50:53]
	v_mfma_f32_16x16x32_bf16 v[38:41], v[178:181], v[216:219], v[38:41]
	v_mfma_f32_16x16x32_bf16 v[34:37], v[186:189], v[216:219], v[34:37]
	v_mfma_f32_16x16x32_bf16 v[22:25], v[178:181], v[224:227], v[22:25]
	v_mfma_f32_16x16x32_bf16 v[18:21], v[186:189], v[224:227], v[18:21]
	v_mfma_f32_16x16x32_bf16 v[6:9], v[178:181], v[232:235], v[6:9]
	v_mfma_f32_16x16x32_bf16 v[2:5], v[186:189], v[232:235], v[2:5]
	s_setprio 0
	s_barrier
	s_cmp_gt_u32 vcc_lo, 13
	s_cbranch_scc0 .LBB0_580
	s_and_b64 vcc, exec, s[36:37]
	s_cbranch_vccz .LBB0_583
	s_barrier
